# small weight matrices (qup/kvup/branch projections) converted with all of a workgroup's tile loads issued together, spread over all 512 workgroups
# baseline (speedup 1.0000x reference)
.LBB0_792:
	s_or_b64 exec, exec, s[4:5]
	v_readlane_b32 s5, v235, 17
	v_lshrrev_b32_e32 v2, 3, v163
	v_and_b32_e32 v3, 7, v163
	v_lshlrev_b32_e32 v3, 4, v3
	s_movk_i32 s0, 0x84
	v_mul_lo_u32 v6, v2, s0
	v_add_u32_e32 v6, v6, v3
	v_and_b32_e32 v9, 31, v163
	v_lshrrev_b32_e32 v18, 5, v163
	s_movk_i32 s0, 0x108
	v_mul_lo_u32 v7, v9, s0
	v_lshl_add_u32 v7, v18, 2, v7
	v_lshlrev_b32_e32 v9, 2, v9
	v_lshlrev_b32_e32 v21, 2, v2
	v_readlane_b32 s6, v246, 0
	s_add_i32 s31, s6, 0x0
	s_cmp_lt_u32 s31, 96
	s_cbranch_scc1 .Lfs_saa0_q
	s_cmp_lt_u32 s31, 224
	s_cbranch_scc1 .Lfs_saa0_kv
	s_sub_u32 s30, s31, 224
	s_lshr_b32 s4, s30, 8
	s_and_b32 s30, s30, 255
	v_readlane_b32 s0, v235, 4
	v_readlane_b32 s1, v235, 5
	v_readlane_b32 s2, v235, 6
	v_readlane_b32 s3, v235, 7
	s_cmp_eq_u32 s4, 1
	s_cselect_b32 s0, s2, s0
	s_cselect_b32 s1, s3, s1
	s_cmp_eq_u32 s4, 2
	s_cselect_b32 s0, s12, s0
	s_cselect_b32 s1, s13, s1
	s_lshl_b32 s2, s5, 21
	s_add_u32 s0, s0, s2
	s_addc_u32 s1, s1, 0
	s_lshl_b32 s38, s4, 20
	s_add_u32 s38, s38, 0xf20000
	s_movk_i32 s7, 0x1000
	s_movk_i32 s8, 0x400
	s_lshr_b32 s39, s30, 5
	s_lshl_b32 s39, s39, 7
	s_and_b32 s4, s30, 31
	s_mov_b32 s29, 0
	s_branch .Lfs_saa0_j
.Lfs_saa0_q:
	v_readlane_b32 s0, v244, 62
	v_readlane_b32 s1, v244, 63
	v_readlane_b32 s2, v244, 60
	v_readlane_b32 s3, v244, 61
	s_mul_i32 s30, s5, 0xc0000
	s_add_u32 s0, s0, s30
	s_addc_u32 s1, s1, 0
	s_lshl_b32 s30, s5, 10
	s_add_u32 s2, s2, s30
	s_addc_u32 s3, s3, 0
	s_mov_b32 s38, 0xe40000
	s_movk_i32 s7, 0xc00
	s_movk_i32 s8, 0x200
	s_mul_hi_u32 s39, s31, 0xaaaaaab
	s_mul_i32 s30, s39, 24
	s_sub_u32 s4, s31, s30
	s_lshl_b32 s39, s39, 7
	s_mov_b32 s29, 1
	s_branch .Lfs_saa0_j
.Lfs_saa0_kv:
	s_sub_u32 s30, s31, 96
	v_readlane_b32 s0, v235, 2
	v_readlane_b32 s1, v235, 3
	v_readlane_b32 s2, v235, 0
	v_readlane_b32 s3, v235, 1
	s_lshl_b32 s4, s5, 20
	s_add_u32 s0, s0, s4
	s_addc_u32 s1, s1, 0
	s_lshl_b32 s4, s5, 10
	s_add_u32 s2, s2, s4
	s_addc_u32 s3, s3, 0
	s_mov_b32 s38, 0xea0000
	s_movk_i32 s7, 0x1000
	s_movk_i32 s8, 0x200
	s_lshr_b32 s39, s30, 5
	s_lshl_b32 s39, s39, 7
	s_and_b32 s4, s30, 31
	s_mov_b32 s29, 1
.Lfs_saa0_j:
	v_mov_b32_e32 v48, 1.0
	v_mov_b32_e32 v49, 1.0
	s_cmp_eq_u32 s29, 0
	s_cbranch_scc1 .Lfs_sa_nog0
	s_lshl_b32 s30, s39, 1
	s_add_u32 s2, s2, s30
	s_addc_u32 s3, s3, 0
	global_load_dword v48, v21, s[2:3]
	global_load_dword v49, v21, s[2:3] offset:128
.Lfs_sa_nog0:
	s_lshr_b32 s30, s39, 1
	s_mul_i32 s30, s30, s7
	s_lshl_b32 s2, s4, 7
	s_add_u32 s30, s30, s2
	s_add_u32 s0, s0, s30
	s_addc_u32 s1, s1, 0
	s_lshl_b32 s30, s7, 5
	s_add_u32 s2, s0, s30
	s_addc_u32 s3, s1, 0
	v_mul_lo_u32 v20, v2, s7
	v_add_u32_e32 v20, v20, v3
	global_load_dwordx4 v[40:43], v20, s[0:1]
	global_load_dwordx4 v[44:47], v20, s[2:3]
	s_add_i32 s31, s6, 0x200
	s_cmp_lt_u32 s31, 992
	s_cbranch_scc0 .Lfs_sa_issued
	s_cmp_lt_u32 s31, 96
	s_cbranch_scc1 .Lfs_saa1_q
	s_cmp_lt_u32 s31, 224
	s_cbranch_scc1 .Lfs_saa1_kv
	s_sub_u32 s30, s31, 224
	s_lshr_b32 s4, s30, 8
	s_and_b32 s30, s30, 255
	v_readlane_b32 s0, v235, 4
	v_readlane_b32 s1, v235, 5
	v_readlane_b32 s2, v235, 6
	v_readlane_b32 s3, v235, 7
	s_cmp_eq_u32 s4, 1
	s_cselect_b32 s0, s2, s0
	s_cselect_b32 s1, s3, s1
	s_cmp_eq_u32 s4, 2
	s_cselect_b32 s0, s12, s0
	s_cselect_b32 s1, s13, s1
	s_lshl_b32 s2, s5, 21
	s_add_u32 s0, s0, s2
	s_addc_u32 s1, s1, 0
	s_lshl_b32 s38, s4, 20
	s_add_u32 s38, s38, 0xf20000
	s_movk_i32 s7, 0x1000
	s_movk_i32 s8, 0x400
	s_lshr_b32 s39, s30, 5
	s_lshl_b32 s39, s39, 7
	s_and_b32 s4, s30, 31
	s_mov_b32 s29, 0
	s_branch .Lfs_saa1_j

.Lfs_saa1_j:
	v_mov_b32_e32 v60, 1.0
	v_mov_b32_e32 v61, 1.0
	s_cmp_eq_u32 s29, 0
	s_cbranch_scc1 .Lfs_sa_nog1
	s_lshl_b32 s30, s39, 1
	s_add_u32 s2, s2, s30
	s_addc_u32 s3, s3, 0
	global_load_dword v60, v21, s[2:3]
	global_load_dword v61, v21, s[2:3] offset:128
.Lfs_sa_nog1:
	s_lshr_b32 s30, s39, 1
	s_mul_i32 s30, s30, s7
	s_lshl_b32 s2, s4, 7
	s_add_u32 s30, s30, s2
	s_add_u32 s0, s0, s30
	s_addc_u32 s1, s1, 0
	s_lshl_b32 s30, s7, 5
	s_add_u32 s2, s0, s30
	s_addc_u32 s3, s1, 0
	v_mul_lo_u32 v20, v2, s7
	v_add_u32_e32 v20, v20, v3
	global_load_dwordx4 v[52:55], v20, s[0:1]
	global_load_dwordx4 v[56:59], v20, s[2:3]
.Lfs_sa_issued:
	s_waitcnt vmcnt(0)
	s_add_i32 s31, s6, 0x0
	s_cmp_lt_u32 s31, 96
	s_cbranch_scc1 .Lfs_sab0_q
	s_cmp_lt_u32 s31, 224
	s_cbranch_scc1 .Lfs_sab0_kv
	s_sub_u32 s30, s31, 224
	s_lshr_b32 s4, s30, 8
	s_and_b32 s30, s30, 255
	v_readlane_b32 s0, v235, 4
	v_readlane_b32 s1, v235, 5
	v_readlane_b32 s2, v235, 6
	v_readlane_b32 s3, v235, 7
	s_cmp_eq_u32 s4, 1
	s_cselect_b32 s0, s2, s0
	s_cselect_b32 s1, s3, s1
	s_cmp_eq_u32 s4, 2
	s_cselect_b32 s0, s12, s0
	s_cselect_b32 s1, s13, s1
	s_lshl_b32 s2, s5, 21
	s_add_u32 s0, s0, s2
	s_addc_u32 s1, s1, 0
	s_lshl_b32 s38, s4, 20
	s_add_u32 s38, s38, 0xf20000
	s_movk_i32 s7, 0x1000
	s_movk_i32 s8, 0x400
	s_lshr_b32 s39, s30, 5
	s_lshl_b32 s39, s39, 7
	s_and_b32 s4, s30, 31
	s_mov_b32 s29, 0
	s_branch .Lfs_sab0_j

.Lfs_sab0_j:
	s_lshl_b32 s30, s4, 5
	s_mul_i32 s30, s30, s8
	s_add_u32 s38, s38, s30
	s_add_u32 s38, s38, s39
	s_add_u32 s38, s38, 0xeb20000
	s_add_u32 s38, s26, s38
	s_addc_u32 s39, s27, 0
	v_mul_f32_e32 v40, v40, v48
	v_mul_f32_e32 v41, v41, v48
	v_mul_f32_e32 v42, v42, v48
	v_mul_f32_e32 v43, v43, v48
	v_mul_f32_e32 v44, v44, v49
	v_mul_f32_e32 v45, v45, v49
	v_mul_f32_e32 v46, v46, v49
	v_mul_f32_e32 v47, v47, v49
	s_barrier
	ds_write2_b32 v6, v40, v41 offset1:1
	ds_write2_b32 v6, v42, v43 offset0:2 offset1:3
	v_add_u32_e32 v19, 0x1080, v6
	ds_write2_b32 v19, v44, v45 offset1:1
	ds_write2_b32 v19, v46, v47 offset0:2 offset1:3
	s_waitcnt lgkmcnt(0)
	s_barrier
	ds_read_b32 v22, v7
	ds_read_b32 v23, v7 offset:132
	ds_read_b32 v24, v7 offset:32
	ds_read_b32 v25, v7 offset:164
	ds_read_b32 v26, v7 offset:64
	ds_read_b32 v27, v7 offset:196
	ds_read_b32 v28, v7 offset:96
	ds_read_b32 v29, v7 offset:228
	v_mul_lo_u32 v20, v18, s8
	v_add_u32_e32 v20, v20, v9
	s_lshl_b32 s0, s8, 3
	s_waitcnt lgkmcnt(0)
	v_cvt_pk_bf16_f32 v22, v22, v23
	v_cvt_pk_bf16_f32 v24, v24, v25
	v_cvt_pk_bf16_f32 v26, v26, v27
	v_cvt_pk_bf16_f32 v28, v28, v29
	global_store_dword v20, v22, s[38:39]
	s_add_u32 s38, s38, s0
	s_addc_u32 s39, s39, 0
	global_store_dword v20, v24, s[38:39]
	s_add_u32 s38, s38, s0
	s_addc_u32 s39, s39, 0
	global_store_dword v20, v26, s[38:39]
	s_add_u32 s38, s38, s0
	s_addc_u32 s39, s39, 0
	global_store_dword v20, v28, s[38:39]
	s_add_i32 s31, s6, 0x200
	s_cmp_lt_u32 s31, 992
	s_cbranch_scc0 .Lfs_sa_done
	s_cmp_lt_u32 s31, 96
	s_cbranch_scc1 .Lfs_sab1_q
	s_cmp_lt_u32 s31, 224
	s_cbranch_scc1 .Lfs_sab1_kv
	s_sub_u32 s30, s31, 224
	s_lshr_b32 s4, s30, 8
	s_and_b32 s30, s30, 255
	v_readlane_b32 s0, v235, 4
	v_readlane_b32 s1, v235, 5
	v_readlane_b32 s2, v235, 6
	v_readlane_b32 s3, v235, 7
	s_cmp_eq_u32 s4, 1
	s_cselect_b32 s0, s2, s0
	s_cselect_b32 s1, s3, s1
	s_cmp_eq_u32 s4, 2
	s_cselect_b32 s0, s12, s0
	s_cselect_b32 s1, s13, s1
	s_lshl_b32 s2, s5, 21
	s_add_u32 s0, s0, s2
	s_addc_u32 s1, s1, 0
	s_lshl_b32 s38, s4, 20
	s_add_u32 s38, s38, 0xf20000
	s_movk_i32 s7, 0x1000
	s_movk_i32 s8, 0x400
	s_lshr_b32 s39, s30, 5
	s_lshl_b32 s39, s39, 7
	s_and_b32 s4, s30, 31
	s_mov_b32 s29, 0
	s_branch .Lfs_sab1_j

.Lfs_sab1_j:
	s_lshl_b32 s30, s4, 5
	s_mul_i32 s30, s30, s8
	s_add_u32 s38, s38, s30
	s_add_u32 s38, s38, s39
	s_add_u32 s38, s38, 0xeb20000
	s_add_u32 s38, s26, s38
	s_addc_u32 s39, s27, 0
	v_mul_f32_e32 v52, v52, v60
	v_mul_f32_e32 v53, v53, v60
	v_mul_f32_e32 v54, v54, v60
	v_mul_f32_e32 v55, v55, v60
	v_mul_f32_e32 v56, v56, v61
	v_mul_f32_e32 v57, v57, v61
	v_mul_f32_e32 v58, v58, v61
	v_mul_f32_e32 v59, v59, v61
	s_barrier
	ds_write2_b32 v6, v52, v53 offset1:1
	ds_write2_b32 v6, v54, v55 offset0:2 offset1:3
	v_add_u32_e32 v19, 0x1080, v6
	ds_write2_b32 v19, v56, v57 offset1:1
	ds_write2_b32 v19, v58, v59 offset0:2 offset1:3
	s_waitcnt lgkmcnt(0)
	s_barrier
	ds_read_b32 v22, v7
	ds_read_b32 v23, v7 offset:132
	ds_read_b32 v24, v7 offset:32
	ds_read_b32 v25, v7 offset:164
	ds_read_b32 v26, v7 offset:64
	ds_read_b32 v27, v7 offset:196
	ds_read_b32 v28, v7 offset:96
	ds_read_b32 v29, v7 offset:228
	v_mul_lo_u32 v20, v18, s8
	v_add_u32_e32 v20, v20, v9
	s_lshl_b32 s0, s8, 3
	s_waitcnt lgkmcnt(0)
	v_cvt_pk_bf16_f32 v22, v22, v23
	v_cvt_pk_bf16_f32 v24, v24, v25
	v_cvt_pk_bf16_f32 v26, v26, v27
	v_cvt_pk_bf16_f32 v28, v28, v29
	global_store_dword v20, v22, s[38:39]
	s_add_u32 s38, s38, s0
	s_addc_u32 s39, s39, 0
	global_store_dword v20, v24, s[38:39]
	s_add_u32 s38, s38, s0
	s_addc_u32 s39, s39, 0
	global_store_dword v20, v26, s[38:39]
	s_add_u32 s38, s38, s0
	s_addc_u32 s39, s39, 0
	global_store_dword v20, v28, s[38:39]
.Lfs_sa_done:
	s_waitcnt vmcnt(0) lgkmcnt(0)
	s_barrier
	s_mov_b32 s0, s26
	s_mov_b32 s1, s27
	s_mov_b64 s[2:3], 0

.LBB0_864:
	s_or_b64 exec, exec, s[4:5]
	s_mov_b32 s5, 0
	v_lshrrev_b32_e32 v2, 3, v163
	v_and_b32_e32 v3, 7, v163
	v_lshlrev_b32_e32 v3, 4, v3
	s_movk_i32 s0, 0x84
	v_mul_lo_u32 v6, v2, s0
	v_add_u32_e32 v6, v6, v3
	v_and_b32_e32 v9, 31, v163
	v_lshrrev_b32_e32 v18, 5, v163
	s_movk_i32 s0, 0x108
	v_mul_lo_u32 v7, v9, s0
	v_lshl_add_u32 v7, v18, 2, v7
	v_lshlrev_b32_e32 v9, 2, v9
	v_lshlrev_b32_e32 v21, 2, v2
	v_readlane_b32 s6, v246, 0
	s_add_i32 s31, s6, 0x0
	s_cmp_lt_u32 s31, 96
	s_cbranch_scc1 .Lfs_sba0_q
	s_cmp_lt_u32 s31, 224
	s_cbranch_scc1 .Lfs_sba0_kv
	s_sub_u32 s30, s31, 224
	s_lshr_b32 s4, s30, 8
	s_and_b32 s30, s30, 255
	v_readlane_b32 s0, v235, 4
	v_readlane_b32 s1, v235, 5
	v_readlane_b32 s2, v235, 6
	v_readlane_b32 s3, v235, 7
	s_cmp_eq_u32 s4, 1
	s_cselect_b32 s0, s2, s0
	s_cselect_b32 s1, s3, s1
	s_cmp_eq_u32 s4, 2
	s_cselect_b32 s0, s12, s0
	s_cselect_b32 s1, s13, s1
	s_lshl_b32 s2, s5, 21
	s_add_u32 s0, s0, s2
	s_addc_u32 s1, s1, 0
	s_lshl_b32 s38, s4, 20
	s_add_u32 s38, s38, 0xf20000
	s_movk_i32 s7, 0x1000
	s_movk_i32 s8, 0x400
	s_lshr_b32 s39, s30, 5
	s_lshl_b32 s39, s39, 7
	s_and_b32 s4, s30, 31
	s_mov_b32 s29, 0
	s_branch .Lfs_sba0_j
